# plus sample recurrence per-token body re-emitted (one batch of LDS reads, four column-group chains interleaved without DPP padding, packed partial-sum dot products)
# speedup vs baseline: 1.0279x; 1.0039x over previous
; #define LAS __attribute__((address_space(3)))
; __device__ __forceinline__ void gdn_sample_item(LAS unsigned char* lds, int item, const bf16_t* qkv, const float* bg, const float* gconv_w, const float* st_gconv, const float* st_grec, bf16_t* zb, const float* gnorm_w, float* srec) {
;     ...
;     for (int tt = 0; tt < DECS; ++tt) {
;         const float a = eas[tt], be = bs[tt];
;         const f32x4 k0 = *(const LAS f32x4*)(ks + tt * 128 + 8 * dki), k1 = *(const LAS f32x4*)(ks + tt * 128 + 8 * dki + 4);
;         const f32x4 q0 = *(const LAS f32x4*)(qs + tt * 128 + 8 * dki), q1 = *(const LAS f32x4*)(qs + tt * 128 + 8 * dki + 4);
; #pragma unroll
;         for (int cc = 0; cc < 4; ++cc) { float part = 0.f;
; #pragma unroll
;             for (int j = 0; j < 8; ++j) { Sr[cc][j] *= a; part += (j < 4 ? k0[j] : k1[j - 4]) * Sr[cc][j]; }
;             part = row16_sum(part);
;             const float uu = be * (vs[tt * 128 + cq + 32 * cc] - part); float po = 0.f;
; #pragma unroll
;             for (int j = 0; j < 8; ++j) { Sr[cc][j] += (j < 4 ? k0[j] : k1[j - 4]) * uu; po += (j < 4 ? q0[j] : q1[j - 4]) * Sr[cc][j]; }
;             po = row16_sum(po);
;             if (dki == 0) os[tt * 128 + cq + 32 * cc] = po; }
.LBB0_729:
	v_mov_b32_e32 v2, s8
	ds_read2_b32 v[68:69], v2 offset1:8
	v_add_u32_e32 v2, s0, v80
	v_add_u32_e32 v82, s0, v81
	ds_read_b128 v[14:17], v2 offset:4096
	ds_read_b128 v[6:9], v2 offset:4112
	ds_read_b32 v84, v82
	ds_read_b32 v85, v82 offset:128
	ds_read_b32 v86, v82 offset:256
	ds_read_b32 v87, v82 offset:384
	ds_read_b128 v[10:13], v2
	ds_read_b128 v[2:5], v2 offset:16
	s_waitcnt lgkmcnt(8)
	v_mov_b32_e32 v88, v69
	v_mov_b32_e32 v89, v69
	v_pk_mul_f32 v[52:53], v[52:53], v[88:89]
	v_pk_mul_f32 v[36:37], v[36:37], v[88:89]
	v_pk_mul_f32 v[66:67], v[66:67], v[88:89]
	v_pk_mul_f32 v[42:43], v[42:43], v[88:89]
	v_pk_mul_f32 v[54:55], v[54:55], v[88:89]
	v_pk_mul_f32 v[38:39], v[38:39], v[88:89]
	v_pk_mul_f32 v[62:63], v[62:63], v[88:89]
	v_pk_mul_f32 v[46:47], v[46:47], v[88:89]
	v_pk_mul_f32 v[58:59], v[58:59], v[88:89]
	v_pk_mul_f32 v[40:41], v[40:41], v[88:89]
	v_pk_mul_f32 v[60:61], v[60:61], v[88:89]
	v_pk_mul_f32 v[48:49], v[48:49], v[88:89]
	v_pk_mul_f32 v[64:65], v[64:65], v[88:89]
	v_pk_mul_f32 v[44:45], v[44:45], v[88:89]
	v_pk_mul_f32 v[56:57], v[56:57], v[88:89]
	v_pk_mul_f32 v[50:51], v[50:51], v[88:89]
	s_waitcnt lgkmcnt(6)
	v_pk_mul_f32 v[90:91], v[52:53], v[14:15]
	v_pk_mul_f32 v[92:93], v[36:37], v[14:15]
	v_pk_mul_f32 v[94:95], v[66:67], v[14:15]
	v_pk_mul_f32 v[96:97], v[42:43], v[14:15]
	v_pk_fma_f32 v[90:91], v[54:55], v[16:17], v[90:91]
	v_pk_fma_f32 v[92:93], v[38:39], v[16:17], v[92:93]
	v_pk_fma_f32 v[94:95], v[62:63], v[16:17], v[94:95]
	v_pk_fma_f32 v[96:97], v[46:47], v[16:17], v[96:97]
	v_pk_fma_f32 v[90:91], v[58:59], v[6:7], v[90:91]
	v_pk_fma_f32 v[92:93], v[40:41], v[6:7], v[92:93]
	v_pk_fma_f32 v[94:95], v[60:61], v[6:7], v[94:95]
	v_pk_fma_f32 v[96:97], v[48:49], v[6:7], v[96:97]
	v_pk_fma_f32 v[90:91], v[64:65], v[8:9], v[90:91]
	v_pk_fma_f32 v[92:93], v[44:45], v[8:9], v[92:93]
	v_pk_fma_f32 v[94:95], v[56:57], v[8:9], v[94:95]
	v_pk_fma_f32 v[96:97], v[50:51], v[8:9], v[96:97]
	v_add_f32_e32 v90, v90, v91
	v_add_f32_e32 v92, v92, v93
	v_add_f32_e32 v94, v94, v95
	v_add_f32_e32 v96, v96, v97
	v_add_f32_dpp v90, v90, v90 quad_perm:[1,0,3,2] row_mask:0xf bank_mask:0xf bound_ctrl:1
	v_add_f32_dpp v92, v92, v92 quad_perm:[1,0,3,2] row_mask:0xf bank_mask:0xf bound_ctrl:1
	v_add_f32_dpp v94, v94, v94 quad_perm:[1,0,3,2] row_mask:0xf bank_mask:0xf bound_ctrl:1
	v_add_f32_dpp v96, v96, v96 quad_perm:[1,0,3,2] row_mask:0xf bank_mask:0xf bound_ctrl:1
	v_add_f32_dpp v90, v90, v90 quad_perm:[2,3,0,1] row_mask:0xf bank_mask:0xf bound_ctrl:1
	v_add_f32_dpp v92, v92, v92 quad_perm:[2,3,0,1] row_mask:0xf bank_mask:0xf bound_ctrl:1
	v_add_f32_dpp v94, v94, v94 quad_perm:[2,3,0,1] row_mask:0xf bank_mask:0xf bound_ctrl:1
	v_add_f32_dpp v96, v96, v96 quad_perm:[2,3,0,1] row_mask:0xf bank_mask:0xf bound_ctrl:1
	v_add_f32_dpp v90, v90, v90 row_ror:4 row_mask:0xf bank_mask:0xf bound_ctrl:1
	v_add_f32_dpp v92, v92, v92 row_ror:4 row_mask:0xf bank_mask:0xf bound_ctrl:1
	v_add_f32_dpp v94, v94, v94 row_ror:4 row_mask:0xf bank_mask:0xf bound_ctrl:1
	v_add_f32_dpp v96, v96, v96 row_ror:4 row_mask:0xf bank_mask:0xf bound_ctrl:1
	v_add_f32_dpp v90, v90, v90 row_ror:8 row_mask:0xf bank_mask:0xf bound_ctrl:1
	v_add_f32_dpp v92, v92, v92 row_ror:8 row_mask:0xf bank_mask:0xf bound_ctrl:1
	v_add_f32_dpp v94, v94, v94 row_ror:8 row_mask:0xf bank_mask:0xf bound_ctrl:1
	v_add_f32_dpp v96, v96, v96 row_ror:8 row_mask:0xf bank_mask:0xf bound_ctrl:1
	s_waitcnt lgkmcnt(2)
; __device__ __forceinline__ void gdn_sample_item(LAS unsigned char* lds, int item, const bf16_t* qkv, const float* bg, const float* gconv_w, const float* st_gconv, const float* st_grec, bf16_t* zb, const float* gnorm_w, float* srec) {
;     ...
;         for (int cc = 0; cc < 4; ++cc) { float part = 0.f;
; #pragma unroll
;             for (int j = 0; j < 8; ++j) { Sr[cc][j] *= a; part += (j < 4 ? k0[j] : k1[j - 4]) * Sr[cc][j]; }
;             part = row16_sum(part);
;             const float uu = be * (vs[tt * 128 + cq + 32 * cc] - part); float po = 0.f;
; #pragma unroll
;             for (int j = 0; j < 8; ++j) { Sr[cc][j] += (j < 4 ? k0[j] : k1[j - 4]) * uu; po += (j < 4 ? q0[j] : q1[j - 4]) * Sr[cc][j]; }
;             po = row16_sum(po);
;             if (dki == 0) os[tt * 128 + cq + 32 * cc] = po; }
;     }
	v_sub_f32_e32 v90, v84, v90
	v_sub_f32_e32 v92, v85, v92
	v_sub_f32_e32 v94, v86, v94
	v_sub_f32_e32 v96, v87, v96
	v_mul_f32_e32 v98, v68, v90
	v_mul_f32_e32 v100, v68, v92
	v_mul_f32_e32 v102, v68, v94
	v_mul_f32_e32 v104, v68, v96
	v_pk_fma_f32 v[52:53], v[14:15], v[98:99], v[52:53] op_sel_hi:[1,0,1]
	v_pk_fma_f32 v[36:37], v[14:15], v[100:101], v[36:37] op_sel_hi:[1,0,1]
	v_pk_fma_f32 v[66:67], v[14:15], v[102:103], v[66:67] op_sel_hi:[1,0,1]
	v_pk_fma_f32 v[42:43], v[14:15], v[104:105], v[42:43] op_sel_hi:[1,0,1]
	v_pk_fma_f32 v[54:55], v[16:17], v[98:99], v[54:55] op_sel_hi:[1,0,1]
	v_pk_fma_f32 v[38:39], v[16:17], v[100:101], v[38:39] op_sel_hi:[1,0,1]
	v_pk_fma_f32 v[62:63], v[16:17], v[102:103], v[62:63] op_sel_hi:[1,0,1]
	v_pk_fma_f32 v[46:47], v[16:17], v[104:105], v[46:47] op_sel_hi:[1,0,1]
	v_pk_fma_f32 v[58:59], v[6:7], v[98:99], v[58:59] op_sel_hi:[1,0,1]
	v_pk_fma_f32 v[40:41], v[6:7], v[100:101], v[40:41] op_sel_hi:[1,0,1]
	v_pk_fma_f32 v[60:61], v[6:7], v[102:103], v[60:61] op_sel_hi:[1,0,1]
	v_pk_fma_f32 v[48:49], v[6:7], v[104:105], v[48:49] op_sel_hi:[1,0,1]
	v_pk_fma_f32 v[64:65], v[8:9], v[98:99], v[64:65] op_sel_hi:[1,0,1]
	v_pk_fma_f32 v[44:45], v[8:9], v[100:101], v[44:45] op_sel_hi:[1,0,1]
	v_pk_fma_f32 v[56:57], v[8:9], v[102:103], v[56:57] op_sel_hi:[1,0,1]
	v_pk_fma_f32 v[50:51], v[8:9], v[104:105], v[50:51] op_sel_hi:[1,0,1]
	s_waitcnt lgkmcnt(0)
	v_pk_mul_f32 v[90:91], v[52:53], v[10:11]
	v_pk_mul_f32 v[92:93], v[36:37], v[10:11]
	v_pk_mul_f32 v[94:95], v[66:67], v[10:11]
	v_pk_mul_f32 v[96:97], v[42:43], v[10:11]
	v_pk_fma_f32 v[90:91], v[54:55], v[12:13], v[90:91]
	v_pk_fma_f32 v[92:93], v[38:39], v[12:13], v[92:93]
	v_pk_fma_f32 v[94:95], v[62:63], v[12:13], v[94:95]
	v_pk_fma_f32 v[96:97], v[46:47], v[12:13], v[96:97]
	v_pk_fma_f32 v[90:91], v[58:59], v[2:3], v[90:91]
	v_pk_fma_f32 v[92:93], v[40:41], v[2:3], v[92:93]
	v_pk_fma_f32 v[94:95], v[60:61], v[2:3], v[94:95]
	v_pk_fma_f32 v[96:97], v[48:49], v[2:3], v[96:97]
	v_pk_fma_f32 v[90:91], v[64:65], v[4:5], v[90:91]
	v_pk_fma_f32 v[92:93], v[44:45], v[4:5], v[92:93]
	v_pk_fma_f32 v[94:95], v[56:57], v[4:5], v[94:95]
	v_pk_fma_f32 v[96:97], v[50:51], v[4:5], v[96:97]
	v_add_f32_e32 v90, v90, v91
	v_add_f32_e32 v92, v92, v93
	v_add_f32_e32 v94, v94, v95
	v_add_f32_e32 v96, v96, v97
	v_add_f32_dpp v90, v90, v90 quad_perm:[1,0,3,2] row_mask:0xf bank_mask:0xf bound_ctrl:1
	v_add_f32_dpp v92, v92, v92 quad_perm:[1,0,3,2] row_mask:0xf bank_mask:0xf bound_ctrl:1
	v_add_f32_dpp v94, v94, v94 quad_perm:[1,0,3,2] row_mask:0xf bank_mask:0xf bound_ctrl:1
	v_add_f32_dpp v96, v96, v96 quad_perm:[1,0,3,2] row_mask:0xf bank_mask:0xf bound_ctrl:1
	v_add_f32_dpp v90, v90, v90 quad_perm:[2,3,0,1] row_mask:0xf bank_mask:0xf bound_ctrl:1
	v_add_f32_dpp v92, v92, v92 quad_perm:[2,3,0,1] row_mask:0xf bank_mask:0xf bound_ctrl:1
	v_add_f32_dpp v94, v94, v94 quad_perm:[2,3,0,1] row_mask:0xf bank_mask:0xf bound_ctrl:1
	v_add_f32_dpp v96, v96, v96 quad_perm:[2,3,0,1] row_mask:0xf bank_mask:0xf bound_ctrl:1
	v_add_f32_dpp v90, v90, v90 row_ror:4 row_mask:0xf bank_mask:0xf bound_ctrl:1
	v_add_f32_dpp v92, v92, v92 row_ror:4 row_mask:0xf bank_mask:0xf bound_ctrl:1
	v_add_f32_dpp v94, v94, v94 row_ror:4 row_mask:0xf bank_mask:0xf bound_ctrl:1
	v_add_f32_dpp v96, v96, v96 row_ror:4 row_mask:0xf bank_mask:0xf bound_ctrl:1
	v_add_f32_dpp v90, v90, v90 row_ror:8 row_mask:0xf bank_mask:0xf bound_ctrl:1
	v_add_f32_dpp v92, v92, v92 row_ror:8 row_mask:0xf bank_mask:0xf bound_ctrl:1
	v_add_f32_dpp v94, v94, v94 row_ror:8 row_mask:0xf bank_mask:0xf bound_ctrl:1
	v_add_f32_dpp v96, v96, v96 row_ror:8 row_mask:0xf bank_mask:0xf bound_ctrl:1
	s_and_saveexec_b64 s[6:7], vcc
	ds_write_b32 v82, v90 offset:4096
	ds_write_b32 v82, v92 offset:4224
	ds_write_b32 v82, v94 offset:4352
	ds_write_b32 v82, v96 offset:4480
	s_branch .LBB0_728
